# stack5 + MLA K/V expansion GEMMs (K=128): both K slices LDS-DMA issued in the tile prologue (after a staging-release barrier) instead of slice 1 at the first loop iteration
# speedup vs baseline: 1.0020x; 1.0020x over previous
; template <bool SW>
; __device__ __forceinline__ void gemm_mainloop(const bf16_t* __restrict__ A, int lda, const bf16_t* __restrict__ Bt, int ldb, int K,
;                                               f32x16 (&acc)[2][2], char* lds, int kstart) {
;     ...
;   for (int i = 0; i < 4; ++i) {
;     const int row = lrow + 8 * i; const int ch = (lane & 7) ^ ((row >> 1) & 7);
;     ap[i] = A + (size_t)row * lda + ch * 8; bp[i] = Bt + (size_t)row * ldb + ch * 8;
;   }
;   char* ldst = lds + (wid * 32) * 128 + lane * 16;
; #pragma unroll
;   for (int i = 0; i < 4; ++i) { glds16(ap[i] + kstart * 64, ldst + i * 1024); glds16(bp[i] + kstart * 64, ldst + 16384 + i * 1024); }
;   asm volatile("s_waitcnt vmcnt(0)" ::: "memory");
;   __syncthreads();
;   const int swz = (l31 >> 1) & 7;
;   const int roffA = (wr * 64 + l31) * 128, roffB = 16384 + (wc * 64 + l31) * 128;
; #pragma unroll 1
;   for (int kt = 0; kt < nk; ++kt) {
;     const bool more = (kt + 1 < nk);
;     if (more) {
;       char* d = ldst + ((kt + 1) & 1) * GEMM_BUF;
;       const int ko = ((kt + 1 + kstart) & (nk - 1)) * 64;
; #pragma unroll
;       for (int i = 0; i < 4; ++i) { glds16(ap[i] + ko, d + i * 1024); glds16(bp[i] + ko, d + 16384 + i * 1024); }
.LBB0_542:
	s_lshl_b32 s38, s42, 7
	s_lshl_b32 s39, s41, 7
	s_and_b64 vcc, exec, s[0:1]
	s_cbranch_vccz .LBB0_560
	s_mul_i32 s0, s38, 0x140
	s_mul_hi_i32 s1, s38, 0x140
	s_add_u32 s0, s28, s0
	s_addc_u32 s1, s29, s1
	v_lshl_add_u64 v[0:1], s[0:1], 0, v[64:65]
	v_mov_b32_e32 v85, v65
	v_readfirstlane_b32 s2, v114
	v_lshl_add_u64 v[0:1], v[0:1], 0, v[84:85]
	s_mov_b32 m0, s2
	v_lshl_add_u64 v[2:3], v[66:67], 1, s[0:1]
	global_load_lds_dwordx4 v[0:1], off
	v_mov_b32_e32 v87, v65
	v_lshl_add_u64 v[104:105], v[2:3], 0, v[86:87]
	v_lshl_add_u64 v[2:3], v[68:69], 1, s[0:1]
	v_lshl_add_u64 v[102:103], v[2:3], 0, v[84:85]
	v_lshl_add_u64 v[2:3], v[70:71], 1, s[0:1]
	v_lshl_add_u64 v[100:101], v[2:3], 0, v[86:87]
	s_cmp_gt_i32 s41, 7
	s_mov_b64 s[0:1], -1
	s_mul_i32 s10, s39, 0x140
	v_lshl_add_u64 v[92:93], v[0:1], 0, s[12:13]
	v_lshl_add_u64 v[94:95], v[104:105], 0, s[12:13]
	v_lshl_add_u64 v[96:97], v[102:103], 0, s[12:13]
	v_lshl_add_u64 v[98:99], v[100:101], 0, s[12:13]
	s_cbranch_scc0 .LBB0_553
	s_mul_hi_u32 s1, s39, 0x140
	s_add_u32 s0, s30, s10
	s_addc_u32 s1, s31, s1
	v_lshl_add_u64 v[0:1], s[0:1], 0, v[64:65]
	v_lshl_add_u64 v[2:3], v[66:67], 1, s[0:1]
	v_lshl_add_u64 v[4:5], v[68:69], 1, s[0:1]
	v_lshl_add_u64 v[6:7], v[70:71], 1, s[0:1]
	v_readfirstlane_b32 s0, v124
	v_lshl_add_u64 v[0:1], v[0:1], 0, v[84:85]
	s_mov_b32 m0, s0
	v_readfirstlane_b32 s0, v125
	global_load_lds_dwordx4 v[0:1], off
	s_mov_b32 m0, s0
	v_readfirstlane_b32 s0, v126
	v_lshl_add_u64 v[2:3], v[2:3], 0, v[86:87]
	global_load_lds_dwordx4 v[104:105], off
	s_mov_b32 m0, s0
	v_readfirstlane_b32 s0, v127
	global_load_lds_dwordx4 v[2:3], off
	s_mov_b32 m0, s0
	v_readfirstlane_b32 s0, v128
	v_lshl_add_u64 v[4:5], v[4:5], 0, v[84:85]
	global_load_lds_dwordx4 v[102:103], off
	s_mov_b32 m0, s0
	v_readfirstlane_b32 s0, v129
	global_load_lds_dwordx4 v[4:5], off
	s_mov_b32 m0, s0
	v_readfirstlane_b32 s0, v130
	v_lshl_add_u64 v[6:7], v[6:7], 0, v[86:87]
	global_load_lds_dwordx4 v[100:101], off
	s_mov_b32 m0, s0
	v_lshl_add_u64 v[106:107], v[0:1], 0, s[12:13]
	global_load_lds_dwordx4 v[6:7], off
	v_mov_b32_e32 v0, 0
	v_lshl_add_u64 v[108:109], v[2:3], 0, s[12:13]
	v_lshl_add_u64 v[110:111], v[4:5], 0, s[12:13]
	v_lshl_add_u64 v[112:113], v[6:7], 0, s[12:13]
	s_mov_b32 s43, 0
	s_mov_b64 s[0:1], 0
	s_mov_b64 s[2:3], -1
	v_mov_b32_e32 v1, v0
	v_mov_b32_e32 v2, v0
	v_mov_b32_e32 v3, v0
	v_mov_b32_e32 v4, v0
	v_mov_b32_e32 v5, v0
	v_mov_b32_e32 v6, v0
	v_mov_b32_e32 v7, v0
	v_mov_b32_e32 v8, v0
	v_mov_b32_e32 v9, v0
	v_mov_b32_e32 v10, v0
	v_mov_b32_e32 v11, v0
	v_mov_b32_e32 v12, v0
	v_mov_b32_e32 v13, v0
	v_mov_b32_e32 v14, v0
	v_mov_b32_e32 v15, v0
	v_mov_b32_e32 v16, v0
	v_mov_b32_e32 v17, v0
	v_mov_b32_e32 v18, v0
	v_mov_b32_e32 v19, v0
	v_mov_b32_e32 v20, v0
	v_mov_b32_e32 v21, v0
	v_mov_b32_e32 v22, v0
	v_mov_b32_e32 v23, v0
	v_mov_b32_e32 v24, v0
	v_mov_b32_e32 v25, v0
	v_mov_b32_e32 v26, v0
	v_mov_b32_e32 v27, v0
	v_mov_b32_e32 v28, v0
	v_mov_b32_e32 v29, v0
	v_mov_b32_e32 v30, v0
	v_mov_b32_e32 v31, v0
	v_mov_b32_e32 v32, v0
	v_mov_b32_e32 v33, v0
	v_mov_b32_e32 v34, v0
	v_mov_b32_e32 v35, v0
	v_mov_b32_e32 v36, v0
	v_mov_b32_e32 v37, v0
	v_mov_b32_e32 v38, v0
	v_mov_b32_e32 v39, v0
	v_mov_b32_e32 v40, v0
	v_mov_b32_e32 v41, v0
	v_mov_b32_e32 v42, v0
	v_mov_b32_e32 v43, v0
	v_mov_b32_e32 v44, v0
	v_mov_b32_e32 v45, v0
	v_mov_b32_e32 v46, v0
	v_mov_b32_e32 v47, v0
	v_mov_b32_e32 v48, v0
	v_mov_b32_e32 v49, v0
	v_mov_b32_e32 v50, v0
	v_mov_b32_e32 v51, v0
	v_mov_b32_e32 v52, v0
	v_mov_b32_e32 v53, v0
	v_mov_b32_e32 v54, v0
	v_mov_b32_e32 v55, v0
	v_mov_b32_e32 v56, v0
	v_mov_b32_e32 v57, v0
	v_mov_b32_e32 v58, v0
	v_mov_b32_e32 v59, v0
	v_mov_b32_e32 v60, v0
	v_mov_b32_e32 v61, v0
	v_mov_b32_e32 v62, v0
	v_mov_b32_e32 v63, v0
	s_waitcnt lgkmcnt(0)
	s_barrier
	v_readfirstlane_b32 s2, v131
	s_mov_b32 m0, s2
	v_readfirstlane_b32 s2, v132
	global_load_lds_dwordx4 v[92:93], off
	s_mov_b32 m0, s2
	v_readfirstlane_b32 s2, v133
	global_load_lds_dwordx4 v[106:107], off
	s_mov_b32 m0, s2
	v_readfirstlane_b32 s2, v134
	global_load_lds_dwordx4 v[94:95], off
	s_mov_b32 m0, s2
	v_readfirstlane_b32 s2, v135
	global_load_lds_dwordx4 v[108:109], off
	s_mov_b32 m0, s2
	v_readfirstlane_b32 s2, v136
	global_load_lds_dwordx4 v[96:97], off
	s_mov_b32 m0, s2
	v_readfirstlane_b32 s2, v137
	global_load_lds_dwordx4 v[110:111], off
	s_mov_b32 m0, s2
	v_readfirstlane_b32 s2, v138
	global_load_lds_dwordx4 v[98:99], off
	s_mov_b32 m0, s2
	s_nop 0
	global_load_lds_dwordx4 v[112:113], off
	s_mov_b64 s[2:3], 0
	s_waitcnt vmcnt(8)
	s_barrier
	s_branch .LBB0_546

; template <bool SW>
; __device__ __forceinline__ void gemm_mainloop(const bf16_t* __restrict__ A, int lda, const bf16_t* __restrict__ Bt, int ldb, int K,
;                                               f32x16 (&acc)[2][2], char* lds, int kstart) {
;     ...
;   for (int i = 0; i < 4; ++i) {
;     const int row = lrow + 8 * i; const int ch = (lane & 7) ^ ((row >> 1) & 7);
;     ap[i] = A + (size_t)row * lda + ch * 8; bp[i] = Bt + (size_t)row * ldb + ch * 8;
;   }
;   char* ldst = lds + (wid * 32) * 128 + lane * 16;
; #pragma unroll
;   for (int i = 0; i < 4; ++i) { glds16(ap[i] + kstart * 64, ldst + i * 1024); glds16(bp[i] + kstart * 64, ldst + 16384 + i * 1024); }
;   asm volatile("s_waitcnt vmcnt(0)" ::: "memory");
;   __syncthreads();
;   const int swz = (l31 >> 1) & 7;
;   const int roffA = (wr * 64 + l31) * 128, roffB = 16384 + (wc * 64 + l31) * 128;
; #pragma unroll 1
;   for (int kt = 0; kt < nk; ++kt) {
;     const bool more = (kt + 1 < nk);
;     if (more) {
;       char* d = ldst + ((kt + 1) & 1) * GEMM_BUF;
;       const int ko = ((kt + 1 + kstart) & (nk - 1)) * 64;
; #pragma unroll
;       for (int i = 0; i < 4; ++i) { glds16(ap[i] + ko, d + i * 1024); glds16(bp[i] + ko, d + 16384 + i * 1024); }
.LBB0_553:
	s_and_b64 vcc, exec, s[0:1]
	s_cbranch_vccz .LBB0_559
	s_mul_hi_i32 s1, s39, 0x140
	s_add_u32 s0, s30, s10
	s_addc_u32 s1, s31, s1
	v_lshl_add_u64 v[0:1], s[0:1], 0, v[64:65]
	v_mov_b32_e32 v85, v65
	v_lshl_add_u64 v[2:3], v[66:67], 1, s[0:1]
	v_lshl_add_u64 v[4:5], v[68:69], 1, s[0:1]
	v_lshl_add_u64 v[6:7], v[70:71], 1, s[0:1]
	v_readfirstlane_b32 s0, v124
	v_lshl_add_u64 v[0:1], v[0:1], 0, v[84:85]
	s_mov_b32 m0, s0
	v_readfirstlane_b32 s0, v125
	v_mov_b32_e32 v87, v65
	global_load_lds_dwordx4 v[0:1], off
	s_mov_b32 m0, s0
	v_readfirstlane_b32 s0, v126
	v_lshl_add_u64 v[2:3], v[2:3], 0, v[86:87]
	global_load_lds_dwordx4 v[104:105], off
	s_mov_b32 m0, s0
	v_readfirstlane_b32 s0, v127
	global_load_lds_dwordx4 v[2:3], off
	s_mov_b32 m0, s0
	v_readfirstlane_b32 s0, v128
	v_lshl_add_u64 v[4:5], v[4:5], 0, v[84:85]
	global_load_lds_dwordx4 v[102:103], off
	s_mov_b32 m0, s0
	v_readfirstlane_b32 s0, v129
	global_load_lds_dwordx4 v[4:5], off
	s_mov_b32 m0, s0
	v_readfirstlane_b32 s0, v130
	v_lshl_add_u64 v[6:7], v[6:7], 0, v[86:87]
	global_load_lds_dwordx4 v[100:101], off
	s_mov_b32 m0, s0
	v_lshl_add_u64 v[100:101], v[0:1], 0, s[12:13]
	global_load_lds_dwordx4 v[6:7], off
	v_mov_b32_e32 v0, 0
	v_lshl_add_u64 v[102:103], v[2:3], 0, s[12:13]
	v_lshl_add_u64 v[104:105], v[4:5], 0, s[12:13]
	v_lshl_add_u64 v[106:107], v[6:7], 0, s[12:13]
	s_mov_b32 s10, 0
	s_mov_b64 s[0:1], 0
	s_mov_b64 s[2:3], -1
	v_mov_b32_e32 v1, v0
	v_mov_b32_e32 v2, v0
	v_mov_b32_e32 v3, v0
	v_mov_b32_e32 v4, v0
	v_mov_b32_e32 v5, v0
	v_mov_b32_e32 v6, v0
	v_mov_b32_e32 v7, v0
	v_mov_b32_e32 v8, v0
	v_mov_b32_e32 v9, v0
	v_mov_b32_e32 v10, v0
	v_mov_b32_e32 v11, v0
	v_mov_b32_e32 v12, v0
	v_mov_b32_e32 v13, v0
	v_mov_b32_e32 v14, v0
	v_mov_b32_e32 v15, v0
	v_mov_b32_e32 v16, v0
	v_mov_b32_e32 v17, v0
	v_mov_b32_e32 v18, v0
	v_mov_b32_e32 v19, v0
	v_mov_b32_e32 v20, v0
	v_mov_b32_e32 v21, v0
	v_mov_b32_e32 v22, v0
	v_mov_b32_e32 v23, v0
	v_mov_b32_e32 v24, v0
	v_mov_b32_e32 v25, v0
	v_mov_b32_e32 v26, v0
	v_mov_b32_e32 v27, v0
	v_mov_b32_e32 v28, v0
	v_mov_b32_e32 v29, v0
	v_mov_b32_e32 v30, v0
	v_mov_b32_e32 v31, v0
	v_mov_b32_e32 v32, v0
	v_mov_b32_e32 v33, v0
	v_mov_b32_e32 v34, v0
	v_mov_b32_e32 v35, v0
	v_mov_b32_e32 v36, v0
	v_mov_b32_e32 v37, v0
	v_mov_b32_e32 v38, v0
	v_mov_b32_e32 v39, v0
	v_mov_b32_e32 v40, v0
	v_mov_b32_e32 v41, v0
	v_mov_b32_e32 v42, v0
	v_mov_b32_e32 v43, v0
	v_mov_b32_e32 v44, v0
	v_mov_b32_e32 v45, v0
	v_mov_b32_e32 v46, v0
	v_mov_b32_e32 v47, v0
	v_mov_b32_e32 v48, v0
	v_mov_b32_e32 v49, v0
	v_mov_b32_e32 v50, v0
	v_mov_b32_e32 v51, v0
	v_mov_b32_e32 v52, v0
	v_mov_b32_e32 v53, v0
	v_mov_b32_e32 v54, v0
	v_mov_b32_e32 v55, v0
	v_mov_b32_e32 v56, v0
	v_mov_b32_e32 v57, v0
	v_mov_b32_e32 v58, v0
	v_mov_b32_e32 v59, v0
	v_mov_b32_e32 v60, v0
	v_mov_b32_e32 v61, v0
	v_mov_b32_e32 v62, v0
	v_mov_b32_e32 v63, v0
	s_waitcnt lgkmcnt(0)
	s_barrier
	v_readfirstlane_b32 s2, v131
	s_mov_b32 m0, s2
	v_readfirstlane_b32 s2, v132
	global_load_lds_dwordx4 v[92:93], off
	s_mov_b32 m0, s2
	v_readfirstlane_b32 s2, v133
	global_load_lds_dwordx4 v[100:101], off
	s_mov_b32 m0, s2
	v_readfirstlane_b32 s2, v134
	global_load_lds_dwordx4 v[94:95], off
	s_mov_b32 m0, s2
	v_readfirstlane_b32 s2, v135
	global_load_lds_dwordx4 v[102:103], off
	s_mov_b32 m0, s2
	v_readfirstlane_b32 s2, v136
	global_load_lds_dwordx4 v[96:97], off
	s_mov_b32 m0, s2
	v_readfirstlane_b32 s2, v137
	global_load_lds_dwordx4 v[104:105], off
	s_mov_b32 m0, s2
	v_readfirstlane_b32 s2, v138
	global_load_lds_dwordx4 v[98:99], off
	s_mov_b32 m0, s2
	s_nop 0
	global_load_lds_dwordx4 v[106:107], off
	s_mov_b64 s[2:3], 0
	s_waitcnt vmcnt(8)
	s_barrier
	s_branch .LBB0_556
